# MLA loop: accumulator seed kept in a persistent 16-register tuple used as MFMA C operand (18 fewer VALU per iteration), on top of barrier hop removal
# speedup vs baseline: 1.0021x; 1.0021x over previous
; DI f32x16 mfma32(bf16x8 a, bf16x8 b, f32x16 c) { return __builtin_amdgcn_mfma_f32_32x32x16_bf16(a, b, c, 0, 0, 0); }
; DI bool softmax_tile(f32x16& s0, f32x16& s1, float& m, float& l, float& alpha, bf16x8* pf, int lane, bool first, bool check) {
;   if (first) {
;     float mx = fmaxf(s0[0], s1[0]);
; #pragma unroll
;     for (int i = 1; i < 16; ++i) mx = fmaxf(mx, fmaxf(s0[i], s1[i]));
;     mx = fmaxf(mx, shx(mx, 32, lane));
;     m += mx;
; #pragma unroll
;     for (int i = 0; i < 16; ++i) { s0[i] -= mx; s1[i] -= mx; }
;   }
;   float sum = 0.f;
; #pragma unroll
;   for (int i = 0; i < 16; ++i) { s0[i] = __builtin_amdgcn_exp2f(s0[i]); sum += s0[i]; }
; #pragma unroll
;   for (int i = 0; i < 16; ++i) { s1[i] = __builtin_amdgcn_exp2f(s1[i]); sum += s1[i]; }
;   l += sum;
;   pf[0] = pack8(s0, 0); pf[1] = pack8(s0, 8); pf[2] = pack8(s1, 0); pf[3] = pack8(s1, 8);
; DI void attn_mla_unit(const Params& p, int b, int h, int qb, char* smem, bool pre, int nh, bool has_next) {
;     ...
;     for (int sub = 0; sub < 2; ++sub) {
;       f32x16 s0, s1;
; #pragma unroll
;       for (int i = 0; i < 16; ++i) { s0[i] = -m; s1[i] = -m; }
;       {
;         bf16x8 kf[12];
; #pragma unroll
;         for (int s = 0; s < 6; ++s) {
;           kf[2 * s] = *(const bf16x8*)(ks + (sub * 64 + r32) * KR + (s * 16 + hh * 8) * 2);
;           kf[2 * s + 1] = *(const bf16x8*)(ks + (sub * 64 + 32 + r32) * KR + (s * 16 + hh * 8) * 2);
;         }
;         __builtin_amdgcn_sched_barrier(0); __builtin_amdgcn_s_setprio(1);
; #pragma unroll
;         for (int s = 0; s < 6; ++s) { s0 = mfma32(kf[2 * s], qf[s], s0); s1 = mfma32(kf[2 * s + 1], qf[s], s1); }
;       __builtin_amdgcn_s_setprio(0);
; }
;       float alpha; bf16x8 pf[4];
;       const bool resc = softmax_tile(s0, s1, m, l, alpha, pf, lane, (kt == 0) && (sub == 0), (sub == 0) && ((kt & 3) == 0));
.LBB0_1481:
	ds_read_b128 v[110:113], v141 offset:13312
	ds_read_b128 v[114:117], v141 offset:13344
	ds_read_b128 v[118:121], v141 offset:19968
	ds_read_b128 v[152:155], v141 offset:20000
	ds_read_b128 v[156:159], v141 offset:13376
	ds_read_b128 v[160:163], v141 offset:13408
	ds_read_b128 v[164:167], v141 offset:20032
	ds_read_b128 v[168:171], v141 offset:20064
	ds_read_b128 v[172:175], v141 offset:13440
	ds_read_b128 v[176:179], v141 offset:13472
	ds_read_b128 v[196:199], v141 offset:20096
	ds_read_b128 v[200:203], v141 offset:20128
	s_add_i32 s34, s34, s44
	s_lshr_b32 s10, s34, 4
	s_sub_i32 s10, s10, s35
	s_lshl_b32 s14, s10, 6
	s_lshl_b32 s9, s35, 6
	v_mul_u32_u24_e32 v149, 0xd0, v33
	s_ashr_i32 s15, s14, 31
	v_add_f32_e32 v33, 0, v35
	v_mul_u32_u24_e32 v148, 0xc0, v34
	v_add_f32_e32 v34, 0, v36
	v_add_f32_e32 v35, v33, v37
	s_cmpk_lt_u32 s34, 0x80
	v_mul_f32_e32 v32, v34, v32
	v_cndmask_b32_e64 v150, v35, v33, s[2:3]
	s_cselect_b64 s[10:11], -1, 0
	s_cmpk_gt_u32 s34, 0x7f
	v_ashrrev_i32_e32 v125, 31, v124
	v_add_u32_e32 v109, 0, v142
	v_add_u32_e32 v122, 0, v143
	v_cndmask_b32_e64 v123, v32, v34, s[2:3]
	s_cselect_b64 s[2:3], -1, 0
	v_xor_b32_e32 v32, 0x80000000, v150
	v_mov_b32_e32 v33, v32
	v_mov_b64_e32 v[220:221], v[32:33]
	v_mov_b64_e32 v[222:223], v[32:33]
	v_mov_b64_e32 v[224:225], v[32:33]
	v_mov_b64_e32 v[226:227], v[32:33]
	v_mov_b64_e32 v[228:229], v[32:33]
	v_mov_b64_e32 v[230:231], v[32:33]
	v_mov_b64_e32 v[232:233], v[32:33]
	v_mov_b64_e32 v[234:235], v[32:33]
	v_mov_b32_e32 v34, v32
	v_mov_b32_e32 v35, v32
	v_mov_b32_e32 v36, v32
	v_mov_b32_e32 v37, v32
	v_mov_b32_e32 v38, v32
	v_mov_b32_e32 v39, v32
	v_mov_b32_e32 v40, v32
	v_mov_b32_e32 v41, v32
	v_mov_b32_e32 v42, v32
	v_mov_b32_e32 v43, v32
	v_mov_b32_e32 v44, v32
	v_mov_b32_e32 v45, v32
	v_mov_b32_e32 v46, v32
	v_mov_b32_e32 v47, v32
	s_setprio 1
	s_waitcnt lgkmcnt(11)
	v_mfma_f32_32x32x16_bf16 v[48:63], v[110:113], v[100:103], v[32:47]
	s_waitcnt lgkmcnt(9)
	v_mfma_f32_32x32x16_bf16 v[32:47], v[118:121], v[100:103], v[32:47]
	v_mfma_f32_32x32x16_bf16 v[48:63], v[114:117], v[96:99], v[48:63]
	s_waitcnt lgkmcnt(8)
	v_mfma_f32_32x32x16_bf16 v[32:47], v[152:155], v[96:99], v[32:47]
	s_waitcnt lgkmcnt(7)
	v_mfma_f32_32x32x16_bf16 v[48:63], v[156:159], v[92:95], v[48:63]
	s_waitcnt lgkmcnt(5)
	v_mfma_f32_32x32x16_bf16 v[32:47], v[164:167], v[92:95], v[32:47]
	v_mfma_f32_32x32x16_bf16 v[48:63], v[160:163], v[88:91], v[48:63]
	s_waitcnt lgkmcnt(4)
	v_mfma_f32_32x32x16_bf16 v[32:47], v[168:171], v[88:91], v[32:47]
	s_waitcnt lgkmcnt(3)
	v_mfma_f32_32x32x16_bf16 v[48:63], v[172:175], v[84:87], v[48:63]
	s_waitcnt lgkmcnt(1)
	v_mfma_f32_32x32x16_bf16 v[32:47], v[196:199], v[84:87], v[32:47]
	v_mfma_f32_32x32x16_bf16 v[48:63], v[176:179], v[80:83], v[48:63]
	s_waitcnt lgkmcnt(0)
	v_mfma_f32_32x32x16_bf16 v[32:47], v[200:203], v[80:83], v[32:47]
	s_setprio 0
	s_nop 8
	v_exp_f32_e32 v48, v48
	v_exp_f32_e32 v49, v49
	v_exp_f32_e32 v50, v50
	v_exp_f32_e32 v51, v51
	v_add_f32_e32 v110, 0, v48
	v_exp_f32_e32 v52, v52
	v_add_f32_e32 v110, v49, v110
	v_exp_f32_e32 v53, v53
	v_add_f32_e32 v110, v50, v110
	v_exp_f32_e32 v54, v54
	v_add_f32_e32 v110, v51, v110
	v_exp_f32_e32 v55, v55
	v_add_f32_e32 v110, v52, v110
	v_exp_f32_e32 v56, v56
	v_add_f32_e32 v110, v53, v110
	v_exp_f32_e32 v57, v57
	v_add_f32_e32 v110, v54, v110
	v_exp_f32_e32 v58, v58
	v_add_f32_e32 v110, v55, v110
	v_exp_f32_e32 v59, v59
	v_add_f32_e32 v110, v56, v110
	v_exp_f32_e32 v60, v60
	v_add_f32_e32 v110, v57, v110
	v_exp_f32_e32 v61, v61
	v_add_f32_e32 v110, v58, v110
	v_exp_f32_e32 v62, v62
	v_add_f32_e32 v110, v59, v110
	v_exp_f32_e32 v63, v63
	v_add_f32_e32 v110, v60, v110
	v_exp_f32_e32 v111, v32
	v_add_f32_e32 v110, v61, v110
	v_add_f32_e32 v110, v62, v110
	v_add_f32_e32 v110, v63, v110
	v_add_f32_e32 v32, v111, v110
	v_exp_f32_e32 v110, v33
	v_exp_f32_e32 v112, v34
	v_exp_f32_e32 v113, v35
	v_exp_f32_e32 v114, v36
	v_add_f32_e32 v32, v110, v32
	v_exp_f32_e32 v115, v37
	v_add_f32_e32 v32, v112, v32
	v_exp_f32_e32 v116, v38
	v_add_f32_e32 v32, v113, v32
	v_exp_f32_e32 v39, v39
	v_add_f32_e32 v32, v114, v32
	v_exp_f32_e32 v33, v40
	v_add_f32_e32 v32, v115, v32
	v_exp_f32_e32 v34, v41
	v_add_f32_e32 v32, v116, v32
	v_exp_f32_e32 v35, v42
	v_add_f32_e32 v32, v39, v32
	v_exp_f32_e32 v36, v43
	v_add_f32_e32 v32, v33, v32
	v_exp_f32_e32 v37, v44
	v_add_f32_e32 v32, v34, v32
	v_exp_f32_e32 v38, v45
	v_add_f32_e32 v32, v35, v32
	v_exp_f32_e32 v40, v46
	v_add_f32_e32 v32, v36, v32
	v_exp_f32_e32 v41, v47
	v_add_f32_e32 v32, v37, v32
	v_add_f32_e32 v32, v38, v32
	v_add_f32_e32 v32, v40, v32
	v_add_f32_e32 v32, v41, v32
	v_add_f32_e32 v153, v123, v32
	v_cvt_pk_bf16_f32 v32, v33, v34
	v_cvt_pk_bf16_f32 v33, v35, v36
	v_cvt_pk_bf16_f32 v34, v37, v38
	v_cvt_pk_bf16_f32 v35, v40, v41
	v_cvt_pk_bf16_f32 v36, v111, v110
	v_cvt_pk_bf16_f32 v37, v112, v113
	v_cvt_pk_bf16_f32 v38, v114, v115
	v_cvt_pk_bf16_f32 v39, v116, v39
	v_cvt_pk_bf16_f32 v40, v56, v57
	v_cvt_pk_bf16_f32 v41, v58, v59
	v_cvt_pk_bf16_f32 v42, v60, v61
	v_cvt_pk_bf16_f32 v43, v62, v63
	v_cvt_pk_bf16_f32 v44, v48, v49
	v_cvt_pk_bf16_f32 v45, v50, v51
	v_cvt_pk_bf16_f32 v46, v52, v53
	v_cvt_pk_bf16_f32 v47, v54, v55
	ds_read_b64_tr_b16 v[48:49], v108 offset:38912
	ds_read_b64_tr_b16 v[50:51], v108 offset:40448
	ds_read_b64_tr_b16 v[52:53], v108 offset:38976
	ds_read_b64_tr_b16 v[54:55], v108 offset:40512
	ds_read_b64_tr_b16 v[56:57], v108 offset:41984
	ds_read_b64_tr_b16 v[58:59], v108 offset:43520
	ds_read_b64_tr_b16 v[60:61], v108 offset:42048
	ds_read_b64_tr_b16 v[62:63], v108 offset:43584
	ds_read_b64_tr_b16 v[110:111], v108 offset:45056
	ds_read_b64_tr_b16 v[112:113], v108 offset:46592
	ds_read_b64_tr_b16 v[114:115], v108 offset:45120
	ds_read_b64_tr_b16 v[116:117], v108 offset:46656
	ds_read_b64_tr_b16 v[118:119], v108 offset:48128
	ds_read_b64_tr_b16 v[120:121], v108 offset:49664
	ds_read_b64_tr_b16 v[154:155], v108 offset:48192
	ds_read_b64_tr_b16 v[156:157], v108 offset:49728
	s_setprio 1
	s_waitcnt lgkmcnt(14)
; DI bool softmax_tile(f32x16& s0, f32x16& s1, float& m, float& l, float& alpha, bf16x8* pf, int lane, bool first, bool check) {
;     ...
;   float sum = 0.f;
; #pragma unroll
;   for (int i = 0; i < 16; ++i) { s0[i] = __builtin_amdgcn_exp2f(s0[i]); sum += s0[i]; }
; #pragma unroll
;   for (int i = 0; i < 16; ++i) { s1[i] = __builtin_amdgcn_exp2f(s1[i]); sum += s1[i]; }
;   l += sum;
;   pf[0] = pack8(s0, 0); pf[1] = pack8(s0, 8); pf[2] = pack8(s1, 0); pf[3] = pack8(s1, 8);
;   alpha = 1.f;
;   if (!check) return false;
;   const float rsum = sum + shx(sum, 32, lane);
; DI void attn_mla_unit(const Params& p, int b, int h, int qb, char* smem, bool pre, int nh, bool has_next) {
;     ...
;   for (int kt = 0; kt < 32; ++kt) {
;     const char* ks = smem + (kt & 1) * STG; const char* vs = ks + 128 * KR;
; #pragma unroll
;     for (int sub = 0; sub < 2; ++sub) {
;       f32x16 s0, s1;
; #pragma unroll
;       for (int i = 0; i < 16; ++i) { s0[i] = -m; s1[i] = -m; }
;       {
;         bf16x8 kf[12];
; #pragma unroll
;         for (int s = 0; s < 6; ++s) {
;           kf[2 * s] = *(const bf16x8*)(ks + (sub * 64 + r32) * KR + (s * 16 + hh * 8) * 2);
;           kf[2 * s + 1] = *(const bf16x8*)(ks + (sub * 64 + 32 + r32) * KR + (s * 16 + hh * 8) * 2);
;         }
;         __builtin_amdgcn_sched_barrier(0); __builtin_amdgcn_s_setprio(1);
; #pragma unroll
;         for (int s = 0; s < 6; ++s) { s0 = mfma32(kf[2 * s], qf[s], s0); s1 = mfma32(kf[2 * s + 1], qf[s], s1); }
;       __builtin_amdgcn_s_setprio(0);
; }
;       float alpha; bf16x8 pf[4];
;       const bool resc = softmax_tile(s0, s1, m, l, alpha, pf, lane, (kt == 0) && (sub == 0), (sub == 0) && ((kt & 3) == 0));
;       {
;         bf16x8 vf[8];
; #pragma unroll
;         for (int s = 0; s < 4; ++s) { vf[2 * s] = ld_vfrag_tr(vs, vbase, VR, sub * 64 + 16 * s, 0); vf[2 * s + 1] = ld_vfrag_tr(vs, vbase, VR, sub * 64 + 16 * s, 32); }
;         __builtin_amdgcn_sched_barrier(0); __builtin_amdgcn_s_setprio(1);
; #pragma unroll
;         for (int s = 0; s < 4; ++s) { O0 = mfma32(vf[2 * s], pf[s], O0); O1 = mfma32(vf[2 * s + 1], pf[s], O1); }
;       __builtin_amdgcn_s_setprio(0);
; }
;       if (resc) { scale16(O0, alpha); scale16(O1, alpha); }
;     }
;     if (kt + 1 < 32) put_stage(smem + ((kt + 1) & 1) * STG);
;     else if (has_next) put_stage(smem);
;     __syncthreads();
;     if (kt + 2 < 32) get_stage(kt + 2);
	v_mfma_f32_32x32x16_bf16 v[16:31], v[48:51], v[44:47], v[16:31]
	s_waitcnt lgkmcnt(12)
	v_mfma_f32_32x32x16_bf16 v[0:15], v[52:55], v[44:47], v[0:15]
	s_waitcnt lgkmcnt(10)
	v_mfma_f32_32x32x16_bf16 v[16:31], v[56:59], v[40:43], v[16:31]
	s_waitcnt lgkmcnt(8)
	v_mfma_f32_32x32x16_bf16 v[0:15], v[60:63], v[40:43], v[0:15]
	s_waitcnt lgkmcnt(6)
	v_mfma_f32_32x32x16_bf16 v[16:31], v[110:113], v[36:39], v[16:31]
	s_waitcnt lgkmcnt(4)
	v_mfma_f32_32x32x16_bf16 v[0:15], v[114:117], v[36:39], v[0:15]
	s_waitcnt lgkmcnt(2)
	v_mfma_f32_32x32x16_bf16 v[16:31], v[118:121], v[32:35], v[16:31]
	s_waitcnt lgkmcnt(0)
	v_mfma_f32_32x32x16_bf16 v[0:15], v[154:157], v[32:35], v[0:15]
	s_setprio 0
	v_add_u32_e32 v151, v109, v138
	v_add3_u32 v32, s48, v139, v138
	s_mov_b32 s12, 0x40000
	s_waitcnt vmcnt(4)
	ds_write_b128 v151, v[64:67] offset:51200
	s_waitcnt vmcnt(3)
	ds_write_b128 v32, v[68:71]
	s_waitcnt vmcnt(2)
	ds_write_b128 v151, v[72:75] offset:64512
	s_waitcnt vmcnt(1)
	ds_write_b128 v32, v[76:79] offset:12288
	v_add_co_u32_e32 v32, vcc, s12, v128
	v_add_u32_e32 v152, v122, v146
	s_nop 0
	v_addc_co_u32_e32 v33, vcc, 0, v129, vcc
	v_add_co_u32_e32 v34, vcc, 0x40000, v130
	s_waitcnt vmcnt(0)
	ds_write_b128 v152, v[104:107] offset:51328
	v_addc_co_u32_e32 v35, vcc, 0, v131, vcc
	s_waitcnt lgkmcnt(0)
	s_barrier
	global_load_dwordx4 v[104:107], v[32:33], off
	global_load_dwordx4 v[108:111], v[34:35], off
	v_add_co_u32_e32 v32, vcc, 0x50000, v128
	v_mov_b32_e32 v135, v145
	s_nop 0
	v_addc_co_u32_e32 v33, vcc, 0, v129, vcc
	v_add_co_u32_e32 v34, vcc, 0x50000, v130
	s_mov_b64 s[12:13], 0x70000
	s_nop 0
	v_addc_co_u32_e32 v35, vcc, 0, v131, vcc
	global_load_dwordx4 v[112:115], v[32:33], off
	global_load_dwordx4 v[116:119], v[34:35], off
	v_add_co_u32_e32 v32, vcc, 0x4000, v126
	s_mov_b32 s18, 2
	s_nop 0
	v_addc_co_u32_e32 v33, vcc, 0, v127, vcc
	global_load_dwordx4 v[120:123], v[32:33], off
	v_lshl_add_u64 v[32:33], v[132:133], 0, v[134:135]
	v_lshl_add_u64 v[64:65], s[28:29], 0, v[32:33]
	s_lshl_b64 s[14:15], s[14:15], 1
.LBB0_1482:
	s_add_i32 s19, s18, -1
	s_bitcmp1_b32 s19, 0
	s_cselect_b32 s16, 0xc800, 0
	s_add_i32 s20, s16, 0
	v_add_u32_e32 v44, s20, v149
	v_add_u32_e32 v67, v44, v144
	ds_read_b128 v[68:71], v67
	ds_read_b128 v[72:75], v67 offset:32
	ds_read_b128 v[76:79], v67 offset:6656
	ds_read_b128 v[132:135], v67 offset:6688
	ds_read_b128 v[154:157], v67 offset:64
	ds_read_b128 v[158:161], v67 offset:96
	ds_read_b128 v[162:165], v67 offset:6720
	ds_read_b128 v[166:169], v67 offset:6752
	ds_read_b128 v[170:173], v67 offset:128
	ds_read_b128 v[174:177], v67 offset:160
	ds_read_b128 v[178:181], v67 offset:6784
	ds_read_b128 v[196:199], v67 offset:6816
	s_and_b32 s16, s19, 3
	s_setprio 1
	s_waitcnt lgkmcnt(8)
	v_mfma_f32_32x32x16_bf16 v[48:63], v[68:71], v[100:103], v[220:235]
	v_mfma_f32_32x32x16_bf16 v[32:47], v[76:79], v[100:103], v[220:235]
	v_mfma_f32_32x32x16_bf16 v[48:63], v[72:75], v[96:99], v[48:63]
	v_mfma_f32_32x32x16_bf16 v[32:47], v[132:135], v[96:99], v[32:47]
	s_waitcnt lgkmcnt(4)
	v_mfma_f32_32x32x16_bf16 v[48:63], v[154:157], v[92:95], v[48:63]
	v_mfma_f32_32x32x16_bf16 v[32:47], v[162:165], v[92:95], v[32:47]
	v_mfma_f32_32x32x16_bf16 v[48:63], v[158:161], v[88:91], v[48:63]
	v_mfma_f32_32x32x16_bf16 v[32:47], v[166:169], v[88:91], v[32:47]
	s_waitcnt lgkmcnt(0)
	v_mfma_f32_32x32x16_bf16 v[48:63], v[170:173], v[84:87], v[48:63]
	v_mfma_f32_32x32x16_bf16 v[32:47], v[178:181], v[84:87], v[32:47]
	v_mfma_f32_32x32x16_bf16 v[48:63], v[174:177], v[80:83], v[48:63]
	v_mfma_f32_32x32x16_bf16 v[32:47], v[196:199], v[80:83], v[32:47]
	s_setprio 0
	s_nop 9
	v_exp_f32_e32 v48, v48
	v_exp_f32_e32 v49, v49
	v_exp_f32_e32 v50, v50
	v_exp_f32_e32 v51, v51
	v_add_f32_e32 v66, 0, v48
	v_exp_f32_e32 v52, v52
	v_add_f32_e32 v66, v49, v66
	v_exp_f32_e32 v53, v53
	v_add_f32_e32 v66, v50, v66
	v_exp_f32_e32 v54, v54
	v_add_f32_e32 v66, v51, v66
	v_exp_f32_e32 v55, v55
	v_add_f32_e32 v66, v52, v66
	v_exp_f32_e32 v56, v56
	v_add_f32_e32 v66, v53, v66
	v_exp_f32_e32 v57, v57
	v_add_f32_e32 v66, v54, v66
	v_exp_f32_e32 v58, v58
	v_add_f32_e32 v66, v55, v66
	v_exp_f32_e32 v59, v59
	v_add_f32_e32 v66, v56, v66
	v_exp_f32_e32 v60, v60
	v_add_f32_e32 v66, v57, v66
	v_exp_f32_e32 v61, v61
	v_add_f32_e32 v66, v58, v66
	v_exp_f32_e32 v62, v62
	v_add_f32_e32 v66, v59, v66
	v_exp_f32_e32 v63, v63
	v_add_f32_e32 v66, v60, v66
	v_exp_f32_e32 v68, v32
	v_add_f32_e32 v66, v61, v66
	v_exp_f32_e32 v33, v33
	v_add_f32_e32 v66, v62, v66
	v_exp_f32_e32 v34, v34
	v_add_f32_e32 v66, v63, v66
	v_exp_f32_e32 v35, v35
	v_add_f32_e32 v32, v68, v66
	v_exp_f32_e32 v36, v36
	v_add_f32_e32 v32, v33, v32
	v_exp_f32_e32 v37, v37
	v_add_f32_e32 v32, v34, v32
	v_exp_f32_e32 v38, v38
	v_add_f32_e32 v32, v35, v32
	v_exp_f32_e32 v39, v39
	v_add_f32_e32 v32, v36, v32
	v_exp_f32_e32 v40, v40
	v_add_f32_e32 v32, v37, v32
	v_exp_f32_e32 v41, v41
	v_add_f32_e32 v32, v38, v32
	v_exp_f32_e32 v42, v42
	v_add_f32_e32 v32, v39, v32
	v_exp_f32_e32 v43, v43
	v_add_f32_e32 v32, v40, v32
	v_exp_f32_e32 v44, v44
	v_add_f32_e32 v32, v41, v32
	v_exp_f32_e32 v45, v45
	v_add_f32_e32 v32, v42, v32
	v_exp_f32_e32 v46, v46
	v_add_f32_e32 v32, v43, v32
	v_exp_f32_e32 v47, v47
	v_add_f32_e32 v32, v44, v32
	v_add_f32_e32 v32, v45, v32
	v_add_f32_e32 v32, v46, v32
	v_add_f32_e32 v32, v47, v32
	s_cmp_lg_u32 s16, 0
	v_add_f32_e32 v66, v153, v32
	s_cbranch_scc0 .LBB0_1484
	s_mov_b64 s[16:17], 0
	v_mov_b32_e32 v32, 1.0
	s_branch .LBB0_1487
.LBB0_1484:
	ds_bpermute_b32 v69, v140, v32
	s_waitcnt lgkmcnt(0)
	v_add_f32_e32 v32, v32, v69
	v_cmp_lt_f32_e32 vcc, s88, v32
	s_cbranch_vccz .LBB0_1486
	v_frexp_exp_i32_f32_e32 v32, v32
	v_add_u32_e32 v32, -7, v32
	v_cvt_f32_i32_e32 v32, v32
	s_mov_b64 s[16:17], -1
	v_cndmask_b32_e32 v69, 0, v32, vcc
	v_exp_f32_e64 v32, -v69
	v_add_f32_e32 v150, v150, v69
	v_sub_f32_e32 v220, v220, v69
	v_sub_f32_e32 v221, v221, v69
	v_sub_f32_e32 v222, v222, v69
	v_sub_f32_e32 v223, v223, v69
	v_sub_f32_e32 v224, v224, v69
	v_sub_f32_e32 v225, v225, v69
	v_sub_f32_e32 v226, v226, v69
	v_sub_f32_e32 v227, v227, v69
	v_sub_f32_e32 v228, v228, v69
	v_sub_f32_e32 v229, v229, v69
	v_sub_f32_e32 v230, v230, v69
	v_sub_f32_e32 v231, v231, v69
	v_sub_f32_e32 v232, v232, v69
	v_sub_f32_e32 v233, v233, v69
	v_sub_f32_e32 v234, v234, v69
	v_sub_f32_e32 v235, v235, v69
	v_mul_f32_e32 v66, v66, v32
	s_branch .LBB0_1487

; DI f32x16 mfma32(bf16x8 a, bf16x8 b, f32x16 c) { return __builtin_amdgcn_mfma_f32_32x32x16_bf16(a, b, c, 0, 0, 0); }
; DI void attn_mla_unit(const Params& p, int b, int h, int qb, char* smem, bool pre, int nh, bool has_next) {
;     ...
;     for (int sub = 0; sub < 2; ++sub) {
;       f32x16 s0, s1;
; #pragma unroll
;       for (int i = 0; i < 16; ++i) { s0[i] = -m; s1[i] = -m; }
;       {
;         bf16x8 kf[12];
; #pragma unroll
;         for (int s = 0; s < 6; ++s) {
;           kf[2 * s] = *(const bf16x8*)(ks + (sub * 64 + r32) * KR + (s * 16 + hh * 8) * 2);
;           kf[2 * s + 1] = *(const bf16x8*)(ks + (sub * 64 + 32 + r32) * KR + (s * 16 + hh * 8) * 2);
;         }
;         __builtin_amdgcn_sched_barrier(0); __builtin_amdgcn_s_setprio(1);
; #pragma unroll
;         for (int s = 0; s < 6; ++s) { s0 = mfma32(kf[2 * s], qf[s], s0); s1 = mfma32(kf[2 * s + 1], qf[s], s1); }
;       __builtin_amdgcn_s_setprio(0);
; }
;       float alpha; bf16x8 pf[4];
;       const bool resc = softmax_tile(s0, s1, m, l, alpha, pf, lane, (kt == 0) && (sub == 0), (sub == 0) && ((kt & 3) == 0));
;       {
;         bf16x8 vf[8];
; #pragma unroll
;         for (int s = 0; s < 4; ++s) { vf[2 * s] = ld_vfrag_tr(vs, vbase, VR, sub * 64 + 16 * s, 0); vf[2 * s + 1] = ld_vfrag_tr(vs, vbase, VR, sub * 64 + 16 * s, 32); }
;         __builtin_amdgcn_sched_barrier(0); __builtin_amdgcn_s_setprio(1);
; #pragma unroll
;         for (int s = 0; s < 4; ++s) { O0 = mfma32(vf[2 * s], pf[s], O0); O1 = mfma32(vf[2 * s + 1], pf[s], O1); }
;       __builtin_amdgcn_s_setprio(0);
; }
;       if (resc) { scale16(O0, alpha); scale16(O1, alpha); }
;     }
;     if (kt + 1 < 32) put_stage(smem + ((kt + 1) & 1) * STG);
;     else if (has_next) put_stage(smem);
;     __syncthreads();
;     if (kt + 2 < 32) get_stage(kt + 2);
;     else if (kt == 30 && has_next) { gk += (nh - h) * 64; gv += (nh - h) * 64; get_stage(0); }
.LBB0_1489:
	ds_read_b128 v[70:73], v67 offset:13312
	ds_read_b128 v[74:77], v67 offset:13344
	ds_read_b128 v[132:135], v67 offset:19968
	ds_read_b128 v[154:157], v67 offset:20000
	ds_read_b128 v[158:161], v67 offset:13376
	ds_read_b128 v[162:165], v67 offset:13408
	ds_read_b128 v[166:169], v67 offset:20032
	ds_read_b128 v[170:173], v67 offset:20064
	ds_read_b128 v[174:177], v67 offset:13440
	ds_read_b128 v[178:181], v67 offset:13472
	ds_read_b128 v[196:199], v67 offset:20096
	ds_read_b128 v[200:203], v67 offset:20128
	s_setprio 1
	s_waitcnt lgkmcnt(8)
	v_mfma_f32_32x32x16_bf16 v[48:63], v[70:73], v[100:103], v[220:235]
	v_mfma_f32_32x32x16_bf16 v[32:47], v[132:135], v[100:103], v[220:235]
	v_mfma_f32_32x32x16_bf16 v[48:63], v[74:77], v[96:99], v[48:63]
	v_mfma_f32_32x32x16_bf16 v[32:47], v[154:157], v[96:99], v[32:47]
	s_waitcnt lgkmcnt(4)
	v_mfma_f32_32x32x16_bf16 v[48:63], v[158:161], v[92:95], v[48:63]
	v_mfma_f32_32x32x16_bf16 v[32:47], v[166:169], v[92:95], v[32:47]
	v_mfma_f32_32x32x16_bf16 v[48:63], v[162:165], v[88:91], v[48:63]
	v_mfma_f32_32x32x16_bf16 v[32:47], v[170:173], v[88:91], v[32:47]
	s_waitcnt lgkmcnt(0)
	v_mfma_f32_32x32x16_bf16 v[48:63], v[174:177], v[84:87], v[48:63]
	v_mfma_f32_32x32x16_bf16 v[32:47], v[196:199], v[84:87], v[32:47]
	v_mfma_f32_32x32x16_bf16 v[48:63], v[178:181], v[80:83], v[48:63]
	v_mfma_f32_32x32x16_bf16 v[32:47], v[200:203], v[80:83], v[32:47]
	s_setprio 0
	ds_read_b64_tr_b16 v[132:133], v68 offset:38912
	ds_read_b64_tr_b16 v[134:135], v68 offset:40448
	ds_read_b64_tr_b16 v[156:157], v68 offset:40512
	ds_read_b64_tr_b16 v[154:155], v68 offset:38976
	ds_read_b64_tr_b16 v[158:159], v68 offset:41984
	ds_read_b64_tr_b16 v[160:161], v68 offset:43520
	ds_read_b64_tr_b16 v[164:165], v68 offset:43584
	ds_read_b64_tr_b16 v[162:163], v68 offset:42048
	ds_read_b64_tr_b16 v[166:167], v68 offset:45056
	ds_read_b64_tr_b16 v[168:169], v68 offset:46592
	ds_read_b64_tr_b16 v[172:173], v68 offset:46656
	ds_read_b64_tr_b16 v[170:171], v68 offset:45120
	ds_read_b64_tr_b16 v[174:175], v68 offset:48128
	ds_read_b64_tr_b16 v[176:177], v68 offset:49664
	ds_read_b64_tr_b16 v[180:181], v68 offset:49728
	ds_read_b64_tr_b16 v[178:179], v68 offset:48192
	v_exp_f32_e32 v40, v40
	v_exp_f32_e32 v41, v41
	v_exp_f32_e32 v42, v42
	v_exp_f32_e32 v43, v43
	v_exp_f32_e32 v44, v44
	v_exp_f32_e32 v45, v45
	v_exp_f32_e32 v46, v46
	v_exp_f32_e32 v47, v47
	v_exp_f32_e32 v48, v48
	v_exp_f32_e32 v49, v49
	v_exp_f32_e32 v50, v50
	v_exp_f32_e32 v51, v51
	v_exp_f32_e32 v52, v52
	v_exp_f32_e32 v53, v53
	v_exp_f32_e32 v54, v54
	v_exp_f32_e32 v55, v55
	v_exp_f32_e32 v56, v56
	v_exp_f32_e32 v57, v57
	v_exp_f32_e32 v58, v58
	v_exp_f32_e32 v59, v59
	v_exp_f32_e32 v60, v60
	v_exp_f32_e32 v61, v61
	v_exp_f32_e32 v62, v62
	v_exp_f32_e32 v63, v63
	v_exp_f32_e32 v67, v32
	v_exp_f32_e32 v69, v33
	v_exp_f32_e32 v70, v34
	v_exp_f32_e32 v71, v35
	v_exp_f32_e32 v36, v36
	v_exp_f32_e32 v37, v37
	v_exp_f32_e32 v38, v38
	v_exp_f32_e32 v39, v39
	v_cvt_pk_bf16_f32 v32, v40, v41
	v_cvt_pk_bf16_f32 v33, v42, v43
	v_cvt_pk_bf16_f32 v34, v44, v45
	v_cvt_pk_bf16_f32 v35, v46, v47
	v_cvt_pk_bf16_f32 v72, v67, v69
	v_cvt_pk_bf16_f32 v73, v70, v71
	v_cvt_pk_bf16_f32 v74, v36, v37
	v_cvt_pk_bf16_f32 v75, v38, v39
	v_cvt_pk_bf16_f32 v76, v56, v57
	v_cvt_pk_bf16_f32 v77, v58, v59
	v_cvt_pk_bf16_f32 v78, v60, v61
	v_cvt_pk_bf16_f32 v79, v62, v63
	v_cvt_pk_bf16_f32 v196, v48, v49
	v_cvt_pk_bf16_f32 v197, v50, v51
	v_cvt_pk_bf16_f32 v198, v52, v53
	v_cvt_pk_bf16_f32 v199, v54, v55
	s_setprio 1
	s_waitcnt lgkmcnt(8)
	v_mfma_f32_32x32x16_bf16 v[16:31], v[132:135], v[196:199], v[16:31]
	v_mfma_f32_32x32x16_bf16 v[0:15], v[154:157], v[196:199], v[0:15]
	v_mfma_f32_32x32x16_bf16 v[16:31], v[158:161], v[76:79], v[16:31]
	v_mfma_f32_32x32x16_bf16 v[0:15], v[162:165], v[76:79], v[0:15]
	s_waitcnt lgkmcnt(0)
	v_mfma_f32_32x32x16_bf16 v[16:31], v[166:169], v[72:75], v[16:31]
	v_mfma_f32_32x32x16_bf16 v[0:15], v[170:173], v[72:75], v[0:15]
	v_mfma_f32_32x32x16_bf16 v[16:31], v[174:177], v[32:35], v[16:31]
	v_mfma_f32_32x32x16_bf16 v[0:15], v[178:181], v[32:35], v[0:15]
	s_setprio 0
	s_bitcmp1_b32 s18, 0
	s_cselect_b32 s16, 0xc800, 0
	s_add_i32 s16, s16, 0
	v_add3_u32 v32, s16, v142, v138
	v_add3_u32 v33, s16, v139, v138
	s_waitcnt vmcnt(4)
	ds_write_b128 v32, v[104:107]
	s_waitcnt vmcnt(2)
	ds_write_b128 v33, v[108:111] offset:26624
	s_waitcnt vmcnt(2)
	ds_write_b128 v32, v[112:115] offset:13312
	s_waitcnt vmcnt(1)
	ds_write_b128 v33, v[116:119] offset:38912
	v_add3_u32 v32, s16, v143, v146
	s_cmp_gt_u32 s19, 29
	s_mov_b64 s[16:17], -1
	s_waitcnt vmcnt(0)
	ds_write_b128 v32, v[120:123] offset:128
	s_waitcnt lgkmcnt(0)
	s_barrier
	s_cbranch_scc0 .LBB0_1493
	s_cmp_lg_u32 s12, 0x410000
	s_cselect_b64 s[16:17], -1, 0
	s_xor_b64 s[20:21], s[10:11], -1
	s_or_b64 s[16:17], s[20:21], s[16:17]
	s_and_b64 vcc, exec, s[16:17]
	v_mov_b64_e32 v[32:33], v[128:129]
	v_mov_b64_e32 v[34:35], v[130:131]
	s_cbranch_vccnz .LBB0_1492
	v_lshl_add_u64 v[32:33], v[128:129], 0, s[14:15]
	v_add_co_u32_e32 v72, vcc, 0x10000, v32
	v_lshl_add_u64 v[34:35], v[130:131], 0, s[14:15]
	s_nop 0
	v_addc_co_u32_e32 v73, vcc, 0, v33, vcc
	global_load_dwordx4 v[104:107], v[32:33], off
	global_load_dwordx4 v[112:115], v[72:73], off
	v_add_co_u32_e32 v72, vcc, 0x10000, v34
	s_nop 1
	v_addc_co_u32_e32 v73, vcc, 0, v35, vcc
	global_load_dwordx4 v[108:111], v[34:35], off
	global_load_dwordx4 v[116:119], v[72:73], off
	global_load_dwordx4 v[120:123], v[126:127], off
